# P0b silu prologue (24 serial loads -> 1 batch) + P1 adaLN prologue batching, on p0map3
# speedup vs baseline: 1.0072x; 1.0072x over previous
.LBB0_89:
	s_or_b64 exec, exec, s[6:7]
	s_movk_i32 s4, 0x3000
	v_cmp_gt_i32_e32 vcc, s4, v36
	v_lshl_add_u32 v1, v36, 2, 0
	s_waitcnt lgkmcnt(0)
	s_barrier
	s_and_saveexec_b64 s[6:7], vcc
	s_cbranch_execz .LBB0_96
	s_load_dwordx2 s[62:63], s[12:13], 0x8
	s_load_dwordx2 s[64:65], s[12:13], 0x18
	v_lshlrev_b32_e32 v2, 2, v36
	s_waitcnt lgkmcnt(0)
	global_load_dword v100, v2, s[62:63]
	global_load_dword v101, v2, s[62:63] offset:2048
	v_add_u32_e32 v3, 0x1000, v2
	global_load_dword v102, v3, s[62:63]
	global_load_dword v103, v3, s[62:63] offset:2048
	v_add_u32_e32 v3, 0x2000, v2
	global_load_dword v104, v3, s[62:63]
	global_load_dword v105, v3, s[62:63] offset:2048
	v_add_u32_e32 v3, 0x3000, v2
	global_load_dword v106, v3, s[62:63]
	global_load_dword v107, v3, s[62:63] offset:2048
	v_add_u32_e32 v3, 0x4000, v2
	global_load_dword v108, v3, s[62:63]
	global_load_dword v109, v3, s[62:63] offset:2048
	v_add_u32_e32 v3, 0x5000, v2
	global_load_dword v110, v3, s[62:63]
	global_load_dword v111, v3, s[62:63] offset:2048
	v_add_u32_e32 v3, 0x6000, v2
	global_load_dword v112, v3, s[62:63]
	global_load_dword v113, v3, s[62:63] offset:2048
	v_add_u32_e32 v3, 0x7000, v2
	global_load_dword v114, v3, s[62:63]
	global_load_dword v115, v3, s[62:63] offset:2048
	global_load_dword v116, v2, s[64:65]
	global_load_dword v117, v2, s[64:65] offset:2048
	v_add_u32_e32 v3, 0x1000, v2
	global_load_dword v118, v3, s[64:65]
	global_load_dword v119, v3, s[64:65] offset:2048
	v_add_u32_e32 v3, 0x2000, v2
	global_load_dword v120, v3, s[64:65]
	global_load_dword v121, v3, s[64:65] offset:2048
	v_add_u32_e32 v3, 0x3000, v2
	global_load_dword v122, v3, s[64:65]
	global_load_dword v123, v3, s[64:65] offset:2048
	s_waitcnt vmcnt(23)
	v_mul_f32_e32 v7, 0xbfb8aa3b, v100
	v_exp_f32_e32 v7, v7
	s_nop 0
	v_add_f32_e32 v4, 1.0, v7
	v_div_scale_f32 v7, s[18:19], v4, v4, v100
	v_rcp_f32_e32 v10, v7
	v_div_scale_f32 v11, vcc, v100, v4, v100
	v_fma_f32 v12, -v7, v10, 1.0
	v_fmac_f32_e32 v10, v12, v10
	v_mul_f32_e32 v12, v11, v10
	v_fma_f32 v13, -v7, v12, v11
	v_fmac_f32_e32 v12, v13, v10
	v_fma_f32 v7, -v7, v12, v11
	v_div_fmas_f32 v7, v7, v10, v12
	v_div_fixup_f32 v4, v7, v4, v100
	ds_write_b32 v1, v4
	s_waitcnt vmcnt(22)
	v_mul_f32_e32 v7, 0xbfb8aa3b, v101
	v_exp_f32_e32 v7, v7
	s_nop 0
	v_add_f32_e32 v4, 1.0, v7
	v_div_scale_f32 v7, s[18:19], v4, v4, v101
	v_rcp_f32_e32 v10, v7
	v_div_scale_f32 v11, vcc, v101, v4, v101
	v_fma_f32 v12, -v7, v10, 1.0
	v_fmac_f32_e32 v10, v12, v10
	v_mul_f32_e32 v12, v11, v10
	v_fma_f32 v13, -v7, v12, v11
	v_fmac_f32_e32 v12, v13, v10
	v_fma_f32 v7, -v7, v12, v11
	v_div_fmas_f32 v7, v7, v10, v12
	v_div_fixup_f32 v4, v7, v4, v101
	ds_write_b32 v1, v4 offset:2048
	s_waitcnt vmcnt(21)
	v_mul_f32_e32 v7, 0xbfb8aa3b, v102
	v_exp_f32_e32 v7, v7
	s_nop 0
	v_add_f32_e32 v4, 1.0, v7
	v_div_scale_f32 v7, s[18:19], v4, v4, v102
	v_rcp_f32_e32 v10, v7
	v_div_scale_f32 v11, vcc, v102, v4, v102
	v_fma_f32 v12, -v7, v10, 1.0
	v_fmac_f32_e32 v10, v12, v10
	v_mul_f32_e32 v12, v11, v10
	v_fma_f32 v13, -v7, v12, v11
	v_fmac_f32_e32 v12, v13, v10
	v_fma_f32 v7, -v7, v12, v11
	v_div_fmas_f32 v7, v7, v10, v12
	v_div_fixup_f32 v4, v7, v4, v102
	ds_write_b32 v1, v4 offset:4096
	s_waitcnt vmcnt(20)
	v_mul_f32_e32 v7, 0xbfb8aa3b, v103
	v_exp_f32_e32 v7, v7
	s_nop 0
	v_add_f32_e32 v4, 1.0, v7
	v_div_scale_f32 v7, s[18:19], v4, v4, v103
	v_rcp_f32_e32 v10, v7
	v_div_scale_f32 v11, vcc, v103, v4, v103
	v_fma_f32 v12, -v7, v10, 1.0
	v_fmac_f32_e32 v10, v12, v10
	v_mul_f32_e32 v12, v11, v10
	v_fma_f32 v13, -v7, v12, v11
	v_fmac_f32_e32 v12, v13, v10
	v_fma_f32 v7, -v7, v12, v11
	v_div_fmas_f32 v7, v7, v10, v12
	v_div_fixup_f32 v4, v7, v4, v103
	ds_write_b32 v1, v4 offset:6144
	s_waitcnt vmcnt(19)
	v_mul_f32_e32 v7, 0xbfb8aa3b, v104
	v_exp_f32_e32 v7, v7
	s_nop 0
	v_add_f32_e32 v4, 1.0, v7
	v_div_scale_f32 v7, s[18:19], v4, v4, v104
	v_rcp_f32_e32 v10, v7
	v_div_scale_f32 v11, vcc, v104, v4, v104
	v_fma_f32 v12, -v7, v10, 1.0
	v_fmac_f32_e32 v10, v12, v10
	v_mul_f32_e32 v12, v11, v10
	v_fma_f32 v13, -v7, v12, v11
	v_fmac_f32_e32 v12, v13, v10
	v_fma_f32 v7, -v7, v12, v11
	v_div_fmas_f32 v7, v7, v10, v12
	v_div_fixup_f32 v4, v7, v4, v104
	ds_write_b32 v1, v4 offset:8192
	s_waitcnt vmcnt(18)
	v_mul_f32_e32 v7, 0xbfb8aa3b, v105
	v_exp_f32_e32 v7, v7
	s_nop 0
	v_add_f32_e32 v4, 1.0, v7
	v_div_scale_f32 v7, s[18:19], v4, v4, v105
	v_rcp_f32_e32 v10, v7
	v_div_scale_f32 v11, vcc, v105, v4, v105
	v_fma_f32 v12, -v7, v10, 1.0
	v_fmac_f32_e32 v10, v12, v10
	v_mul_f32_e32 v12, v11, v10
	v_fma_f32 v13, -v7, v12, v11
	v_fmac_f32_e32 v12, v13, v10
	v_fma_f32 v7, -v7, v12, v11
	v_div_fmas_f32 v7, v7, v10, v12
	v_div_fixup_f32 v4, v7, v4, v105
	ds_write_b32 v1, v4 offset:10240
	s_waitcnt vmcnt(17)
	v_mul_f32_e32 v7, 0xbfb8aa3b, v106
	v_exp_f32_e32 v7, v7
	s_nop 0
	v_add_f32_e32 v4, 1.0, v7
	v_div_scale_f32 v7, s[18:19], v4, v4, v106
	v_rcp_f32_e32 v10, v7
	v_div_scale_f32 v11, vcc, v106, v4, v106
	v_fma_f32 v12, -v7, v10, 1.0
	v_fmac_f32_e32 v10, v12, v10
	v_mul_f32_e32 v12, v11, v10
	v_fma_f32 v13, -v7, v12, v11
	v_fmac_f32_e32 v12, v13, v10
	v_fma_f32 v7, -v7, v12, v11
	v_div_fmas_f32 v7, v7, v10, v12
	v_div_fixup_f32 v4, v7, v4, v106
	ds_write_b32 v1, v4 offset:12288
	s_waitcnt vmcnt(16)
	v_mul_f32_e32 v7, 0xbfb8aa3b, v107
	v_exp_f32_e32 v7, v7
	s_nop 0
	v_add_f32_e32 v4, 1.0, v7
	v_div_scale_f32 v7, s[18:19], v4, v4, v107
	v_rcp_f32_e32 v10, v7
	v_div_scale_f32 v11, vcc, v107, v4, v107
	v_fma_f32 v12, -v7, v10, 1.0
	v_fmac_f32_e32 v10, v12, v10
	v_mul_f32_e32 v12, v11, v10
	v_fma_f32 v13, -v7, v12, v11
	v_fmac_f32_e32 v12, v13, v10
	v_fma_f32 v7, -v7, v12, v11
	v_div_fmas_f32 v7, v7, v10, v12
	v_div_fixup_f32 v4, v7, v4, v107
	ds_write_b32 v1, v4 offset:14336
	s_waitcnt vmcnt(15)
	v_mul_f32_e32 v7, 0xbfb8aa3b, v108
	v_exp_f32_e32 v7, v7
	s_nop 0
	v_add_f32_e32 v4, 1.0, v7
	v_div_scale_f32 v7, s[18:19], v4, v4, v108
	v_rcp_f32_e32 v10, v7
	v_div_scale_f32 v11, vcc, v108, v4, v108
	v_fma_f32 v12, -v7, v10, 1.0
	v_fmac_f32_e32 v10, v12, v10
	v_mul_f32_e32 v12, v11, v10
	v_fma_f32 v13, -v7, v12, v11
	v_fmac_f32_e32 v12, v13, v10
	v_fma_f32 v7, -v7, v12, v11
	v_div_fmas_f32 v7, v7, v10, v12
	v_div_fixup_f32 v4, v7, v4, v108
	ds_write_b32 v1, v4 offset:16384
	s_waitcnt vmcnt(14)
	v_mul_f32_e32 v7, 0xbfb8aa3b, v109
	v_exp_f32_e32 v7, v7
	s_nop 0
	v_add_f32_e32 v4, 1.0, v7
	v_div_scale_f32 v7, s[18:19], v4, v4, v109
	v_rcp_f32_e32 v10, v7
	v_div_scale_f32 v11, vcc, v109, v4, v109
	v_fma_f32 v12, -v7, v10, 1.0
	v_fmac_f32_e32 v10, v12, v10
	v_mul_f32_e32 v12, v11, v10
	v_fma_f32 v13, -v7, v12, v11
	v_fmac_f32_e32 v12, v13, v10
	v_fma_f32 v7, -v7, v12, v11
	v_div_fmas_f32 v7, v7, v10, v12
	v_div_fixup_f32 v4, v7, v4, v109
	ds_write_b32 v1, v4 offset:18432
	s_waitcnt vmcnt(13)
	v_mul_f32_e32 v7, 0xbfb8aa3b, v110
	v_exp_f32_e32 v7, v7
	s_nop 0
	v_add_f32_e32 v4, 1.0, v7
	v_div_scale_f32 v7, s[18:19], v4, v4, v110
	v_rcp_f32_e32 v10, v7
	v_div_scale_f32 v11, vcc, v110, v4, v110
	v_fma_f32 v12, -v7, v10, 1.0
	v_fmac_f32_e32 v10, v12, v10
	v_mul_f32_e32 v12, v11, v10
	v_fma_f32 v13, -v7, v12, v11
	v_fmac_f32_e32 v12, v13, v10
	v_fma_f32 v7, -v7, v12, v11
	v_div_fmas_f32 v7, v7, v10, v12
	v_div_fixup_f32 v4, v7, v4, v110
	ds_write_b32 v1, v4 offset:20480
	s_waitcnt vmcnt(12)
	v_mul_f32_e32 v7, 0xbfb8aa3b, v111
	v_exp_f32_e32 v7, v7
	s_nop 0
	v_add_f32_e32 v4, 1.0, v7
	v_div_scale_f32 v7, s[18:19], v4, v4, v111
	v_rcp_f32_e32 v10, v7
	v_div_scale_f32 v11, vcc, v111, v4, v111
	v_fma_f32 v12, -v7, v10, 1.0
	v_fmac_f32_e32 v10, v12, v10
	v_mul_f32_e32 v12, v11, v10
	v_fma_f32 v13, -v7, v12, v11
	v_fmac_f32_e32 v12, v13, v10
	v_fma_f32 v7, -v7, v12, v11
	v_div_fmas_f32 v7, v7, v10, v12
	v_div_fixup_f32 v4, v7, v4, v111
	ds_write_b32 v1, v4 offset:22528
	s_waitcnt vmcnt(11)
	v_mul_f32_e32 v7, 0xbfb8aa3b, v112
	v_exp_f32_e32 v7, v7
	s_nop 0
	v_add_f32_e32 v4, 1.0, v7
	v_div_scale_f32 v7, s[18:19], v4, v4, v112
	v_rcp_f32_e32 v10, v7
	v_div_scale_f32 v11, vcc, v112, v4, v112
	v_fma_f32 v12, -v7, v10, 1.0
	v_fmac_f32_e32 v10, v12, v10
	v_mul_f32_e32 v12, v11, v10
	v_fma_f32 v13, -v7, v12, v11
	v_fmac_f32_e32 v12, v13, v10
	v_fma_f32 v7, -v7, v12, v11
	v_div_fmas_f32 v7, v7, v10, v12
	v_div_fixup_f32 v4, v7, v4, v112
	ds_write_b32 v1, v4 offset:24576
	s_waitcnt vmcnt(10)
	v_mul_f32_e32 v7, 0xbfb8aa3b, v113
	v_exp_f32_e32 v7, v7
	s_nop 0
	v_add_f32_e32 v4, 1.0, v7
	v_div_scale_f32 v7, s[18:19], v4, v4, v113
	v_rcp_f32_e32 v10, v7
	v_div_scale_f32 v11, vcc, v113, v4, v113
	v_fma_f32 v12, -v7, v10, 1.0
	v_fmac_f32_e32 v10, v12, v10
	v_mul_f32_e32 v12, v11, v10
	v_fma_f32 v13, -v7, v12, v11
	v_fmac_f32_e32 v12, v13, v10
	v_fma_f32 v7, -v7, v12, v11
	v_div_fmas_f32 v7, v7, v10, v12
	v_div_fixup_f32 v4, v7, v4, v113
	ds_write_b32 v1, v4 offset:26624
	s_waitcnt vmcnt(9)
	v_mul_f32_e32 v7, 0xbfb8aa3b, v114
	v_exp_f32_e32 v7, v7
	s_nop 0
	v_add_f32_e32 v4, 1.0, v7
	v_div_scale_f32 v7, s[18:19], v4, v4, v114
	v_rcp_f32_e32 v10, v7
	v_div_scale_f32 v11, vcc, v114, v4, v114
	v_fma_f32 v12, -v7, v10, 1.0
	v_fmac_f32_e32 v10, v12, v10
	v_mul_f32_e32 v12, v11, v10
	v_fma_f32 v13, -v7, v12, v11
	v_fmac_f32_e32 v12, v13, v10
	v_fma_f32 v7, -v7, v12, v11
	v_div_fmas_f32 v7, v7, v10, v12
	v_div_fixup_f32 v4, v7, v4, v114
	ds_write_b32 v1, v4 offset:28672
	s_waitcnt vmcnt(8)
	v_mul_f32_e32 v7, 0xbfb8aa3b, v115
	v_exp_f32_e32 v7, v7
	s_nop 0
	v_add_f32_e32 v4, 1.0, v7
	v_div_scale_f32 v7, s[18:19], v4, v4, v115
	v_rcp_f32_e32 v10, v7
	v_div_scale_f32 v11, vcc, v115, v4, v115
	v_fma_f32 v12, -v7, v10, 1.0
	v_fmac_f32_e32 v10, v12, v10
	v_mul_f32_e32 v12, v11, v10
	v_fma_f32 v13, -v7, v12, v11
	v_fmac_f32_e32 v12, v13, v10
	v_fma_f32 v7, -v7, v12, v11
	v_div_fmas_f32 v7, v7, v10, v12
	v_div_fixup_f32 v4, v7, v4, v115
	ds_write_b32 v1, v4 offset:30720
	s_waitcnt vmcnt(7)
	v_mul_f32_e32 v7, 0xbfb8aa3b, v116
	v_exp_f32_e32 v7, v7
	s_nop 0
	v_add_f32_e32 v4, 1.0, v7
	v_div_scale_f32 v7, s[18:19], v4, v4, v116
	v_rcp_f32_e32 v10, v7
	v_div_scale_f32 v11, vcc, v116, v4, v116
	v_fma_f32 v12, -v7, v10, 1.0
	v_fmac_f32_e32 v10, v12, v10
	v_mul_f32_e32 v12, v11, v10
	v_fma_f32 v13, -v7, v12, v11
	v_fmac_f32_e32 v12, v13, v10
	v_fma_f32 v7, -v7, v12, v11
	v_div_fmas_f32 v7, v7, v10, v12
	v_div_fixup_f32 v4, v7, v4, v116
	ds_write_b32 v1, v4 offset:32768
	s_waitcnt vmcnt(6)
	v_mul_f32_e32 v7, 0xbfb8aa3b, v117
	v_exp_f32_e32 v7, v7
	s_nop 0
	v_add_f32_e32 v4, 1.0, v7
	v_div_scale_f32 v7, s[18:19], v4, v4, v117
	v_rcp_f32_e32 v10, v7
	v_div_scale_f32 v11, vcc, v117, v4, v117
	v_fma_f32 v12, -v7, v10, 1.0
	v_fmac_f32_e32 v10, v12, v10
	v_mul_f32_e32 v12, v11, v10
	v_fma_f32 v13, -v7, v12, v11
	v_fmac_f32_e32 v12, v13, v10
	v_fma_f32 v7, -v7, v12, v11
	v_div_fmas_f32 v7, v7, v10, v12
	v_div_fixup_f32 v4, v7, v4, v117
	ds_write_b32 v1, v4 offset:34816
	s_waitcnt vmcnt(5)
	v_mul_f32_e32 v7, 0xbfb8aa3b, v118
	v_exp_f32_e32 v7, v7
	s_nop 0
	v_add_f32_e32 v4, 1.0, v7
	v_div_scale_f32 v7, s[18:19], v4, v4, v118
	v_rcp_f32_e32 v10, v7
	v_div_scale_f32 v11, vcc, v118, v4, v118
	v_fma_f32 v12, -v7, v10, 1.0
	v_fmac_f32_e32 v10, v12, v10
	v_mul_f32_e32 v12, v11, v10
	v_fma_f32 v13, -v7, v12, v11
	v_fmac_f32_e32 v12, v13, v10
	v_fma_f32 v7, -v7, v12, v11
	v_div_fmas_f32 v7, v7, v10, v12
	v_div_fixup_f32 v4, v7, v4, v118
	ds_write_b32 v1, v4 offset:36864
	s_waitcnt vmcnt(4)
	v_mul_f32_e32 v7, 0xbfb8aa3b, v119
	v_exp_f32_e32 v7, v7
	s_nop 0
	v_add_f32_e32 v4, 1.0, v7
	v_div_scale_f32 v7, s[18:19], v4, v4, v119
	v_rcp_f32_e32 v10, v7
	v_div_scale_f32 v11, vcc, v119, v4, v119
	v_fma_f32 v12, -v7, v10, 1.0
	v_fmac_f32_e32 v10, v12, v10
	v_mul_f32_e32 v12, v11, v10
	v_fma_f32 v13, -v7, v12, v11
	v_fmac_f32_e32 v12, v13, v10
	v_fma_f32 v7, -v7, v12, v11
	v_div_fmas_f32 v7, v7, v10, v12
	v_div_fixup_f32 v4, v7, v4, v119
	ds_write_b32 v1, v4 offset:38912
	s_waitcnt vmcnt(3)
	v_mul_f32_e32 v7, 0xbfb8aa3b, v120
	v_exp_f32_e32 v7, v7
	s_nop 0
	v_add_f32_e32 v4, 1.0, v7
	v_div_scale_f32 v7, s[18:19], v4, v4, v120
	v_rcp_f32_e32 v10, v7
	v_div_scale_f32 v11, vcc, v120, v4, v120
	v_fma_f32 v12, -v7, v10, 1.0
	v_fmac_f32_e32 v10, v12, v10
	v_mul_f32_e32 v12, v11, v10
	v_fma_f32 v13, -v7, v12, v11
	v_fmac_f32_e32 v12, v13, v10
	v_fma_f32 v7, -v7, v12, v11
	v_div_fmas_f32 v7, v7, v10, v12
	v_div_fixup_f32 v4, v7, v4, v120
	ds_write_b32 v1, v4 offset:40960
	s_waitcnt vmcnt(2)
	v_mul_f32_e32 v7, 0xbfb8aa3b, v121
	v_exp_f32_e32 v7, v7
	s_nop 0
	v_add_f32_e32 v4, 1.0, v7
	v_div_scale_f32 v7, s[18:19], v4, v4, v121
	v_rcp_f32_e32 v10, v7
	v_div_scale_f32 v11, vcc, v121, v4, v121
	v_fma_f32 v12, -v7, v10, 1.0
	v_fmac_f32_e32 v10, v12, v10
	v_mul_f32_e32 v12, v11, v10
	v_fma_f32 v13, -v7, v12, v11
	v_fmac_f32_e32 v12, v13, v10
	v_fma_f32 v7, -v7, v12, v11
	v_div_fmas_f32 v7, v7, v10, v12
	v_div_fixup_f32 v4, v7, v4, v121
	ds_write_b32 v1, v4 offset:43008
	s_waitcnt vmcnt(1)
	v_mul_f32_e32 v7, 0xbfb8aa3b, v122
	v_exp_f32_e32 v7, v7
	s_nop 0
	v_add_f32_e32 v4, 1.0, v7
	v_div_scale_f32 v7, s[18:19], v4, v4, v122
	v_rcp_f32_e32 v10, v7
	v_div_scale_f32 v11, vcc, v122, v4, v122
	v_fma_f32 v12, -v7, v10, 1.0
	v_fmac_f32_e32 v10, v12, v10
	v_mul_f32_e32 v12, v11, v10
	v_fma_f32 v13, -v7, v12, v11
	v_fmac_f32_e32 v12, v13, v10
	v_fma_f32 v7, -v7, v12, v11
	v_div_fmas_f32 v7, v7, v10, v12
	v_div_fixup_f32 v4, v7, v4, v122
	ds_write_b32 v1, v4 offset:45056
	s_waitcnt vmcnt(0)
	v_mul_f32_e32 v7, 0xbfb8aa3b, v123
	v_exp_f32_e32 v7, v7
	s_nop 0
	v_add_f32_e32 v4, 1.0, v7
	v_div_scale_f32 v7, s[18:19], v4, v4, v123
	v_rcp_f32_e32 v10, v7
	v_div_scale_f32 v11, vcc, v123, v4, v123
	v_fma_f32 v12, -v7, v10, 1.0
	v_fmac_f32_e32 v10, v12, v10
	v_mul_f32_e32 v12, v11, v10
	v_fma_f32 v13, -v7, v12, v11
	v_fmac_f32_e32 v12, v13, v10
	v_fma_f32 v7, -v7, v12, v11
	v_div_fmas_f32 v7, v7, v10, v12
	v_div_fixup_f32 v4, v7, v4, v123
	ds_write_b32 v1, v4 offset:47104
